# attention kv loops: wave-uniform ballot trimmed (6 sites), MLA ones operand hoisted, diff far-tile bias constants kept in SGPRs instead of per-step LDS reads
# speedup vs baseline: 1.0144x; 1.0020x over previous
; #define LAS __attribute__((address_space(3)))
; #define FA_LOADK(kt) do { _Pragma("unroll") for (int i_ = 0; i_ < NKI; ++i_) kreg[i_] = *(const u32x4*)(ksrc[i_] + (size_t)(unsigned)(kt) * kstep[i_]); } while (0)
; #define FA_LOADV(kt) do { _Pragma("unroll") for (int i_ = 0; i_ < NVI; ++i_) vreg[i_] = *(const u32x4*)(vsrc0 + (size_t)(unsigned)(kt) * vstep + (size_t)i_ * vrowoff); } while (0)
; #define FA_STOREK(buf) do { _Pragma("unroll") for (int i_ = 0; i_ < NKI; ++i_) { if (kval[i_]) *(LAS u32x4*)(Kl + (buf) * KBUF + kdst[i_]) = kreg[i_]; } } while (0)
; #define FA_STOREV(buf) do { _Pragma("unroll") for (int i_ = 0; i_ < NVI; ++i_) *(LAS u32x4*)(Vl + (buf) * VBUF + vdst0 + i_ * VDSTOFF) = vreg[i_]; } while (0)
;     ...
;     f32x16 zero16;
; #pragma unroll
;     for (int r = 0; r < 16; ++r) zero16[r] = 0.f;
;     f32x16 pA0 = zero16, pA1 = zero16, pB0 = zero16, pB1 = zero16;
;     constexpr bool VPRE = (DV <= 64); constexpr int KD = (DV <= 64) ? 3 : 2;
;     constexpr bool NEGM = (MODE != 1);
;     f32x16 negc = zero16; float cbs = 0.f, pend = 0.f; bool pendf = false;
;     if (NEGM) mrun = 0.f;
;     if (!RES) {
;         u32x4 k2_[NKI];
;         FA_LOADK(kt_lo); FA_LOADV(kt_lo);
; #pragma unroll
;         for (int i_ = 0; i_ < NKI; ++i_) k2_[i_] = *(const u32x4*)(ksrc[i_] + (size_t)(unsigned)(kt_lo + 1) * kstep[i_]);
;         FA_STOREK(0); FA_STOREV(0);
; #pragma unroll
;         for (int i_ = 0; i_ < NKI; ++i_) { if (kval[i_]) *(LAS u32x4*)(Kl + KBUF + kdst[i_]) = k2_[i_]; }
;         __syncthreads();
;         if (NEGM) { if (MODE == 2) {     const int tl0 = 64 * kt_lo; float c0_ = 0.f; if (tl0 + 63 - qw0 <= -128) c0_ = lut[0]; else if (tl0 - (qw0 + 31) >= 128) c0_ = lut[511]; cbs = c0_;
; #pragma unroll
;         for (int r_ = 0; r_ < 16; ++r_) negc[r_] = c0_; } }
;         FA_QK(pA0, pA1, 0, negc);
;         __syncthreads();
;     } else {
;         FA_QK(pA0, pA1, kt_lo - win_lo, zero16);
;     }
.LBB0_731:
	s_or_b64 exec, exec, s[14:15]
	s_waitcnt vmcnt(0)
	v_and_b32_e32 v2, 31, v28
	v_lshlrev_b32_e32 v3, 4, v28
	v_lshlrev_b32_e32 v4, 1, v28
	v_mad_u32_u24 v2, v2, s26, 0
	v_and_b32_e32 v3, 0xc0, v3
	v_and_b32_e32 v14, 32, v4
	v_lshlrev_b32_e32 v4, 3, v28
	v_add_u32_e32 v219, v2, v0
	v_and_b32_e32 v15, 24, v4
	v_lshl_or_b32 v16, v29, 8, v3
	s_waitcnt lgkmcnt(0)
	s_barrier
	ds_read_b128 v[2:5], v219 offset:6656
	ds_read_b128 v[6:9], v219
	ds_read_b128 v[10:13], v219 offset:32
	s_waitcnt lgkmcnt(2)
	v_mfma_f32_32x32x16_bf16 v[34:49], v[2:5], v[130:133], 0
	ds_read_b128 v[2:5], v219 offset:6688
	s_lshr_b32 s4, s20, 3
	s_and_b32 s4, s4, 15
	s_lshl_b32 s4, s4, 8
	s_add_u32 s0, s4, s0
	s_addc_u32 s1, 0, s1
	v_or3_b32 v32, v16, v14, v15
	s_waitcnt lgkmcnt(2)
	v_mfma_f32_32x32x16_bf16 v[50:65], v[6:9], v[130:133], 0
	v_mov_b32_e32 v14, v1
	v_mov_b32_e32 v15, v1
	v_mov_b32_e32 v16, v1
	v_mov_b32_e32 v17, v1
	v_mov_b32_e32 v22, v1
	v_mov_b32_e32 v23, v1
	v_mov_b32_e32 v24, v1
	s_waitcnt lgkmcnt(1)
	v_mfma_f32_32x32x16_bf16 v[50:65], v[10:13], v[134:137], v[50:65]
	v_mov_b32_e32 v10, v1
	v_mov_b32_e32 v11, v1
	v_mov_b32_e32 v12, v1
	v_mov_b32_e32 v13, v1
	v_mov_b32_e32 v25, v1
	v_mov_b32_e32 v26, v1
	v_mov_b32_e32 v27, v1
	s_waitcnt lgkmcnt(0)
	v_mfma_f32_32x32x16_bf16 v[34:49], v[2:5], v[134:137], v[34:49]
	ds_read_b128 v[2:5], v219 offset:6720
	ds_read_b128 v[6:9], v219 offset:64
	v_mov_b32_e32 v28, v1
	v_mov_b32_e32 v29, v1
	v_mov_b32_e32 v30, v1
	v_mov_b32_e32 v31, v1
	v_mov_b32_e32 v0, v1
	v_mov_b32_e32 v220, 0
	s_waitcnt lgkmcnt(0)
	v_mfma_f32_32x32x16_bf16 v[50:65], v[6:9], v[138:141], v[50:65]
	v_add_u32_e32 v221, 0, v32
	s_mov_b32 s16, -2
	v_mov_b32_e32 v222, 0
	v_mov_b32_e32 v191, 0
	v_mov_b32_e32 v216, 0
	v_mov_b32_e32 v114, 0
	v_mfma_f32_32x32x16_bf16 v[34:49], v[2:5], v[138:141], v[34:49]
	ds_read_b128 v[2:5], v219 offset:6752
	ds_read_b128 v[6:9], v219 offset:96
	v_mov_b32_e32 v115, v220
	v_mov_b32_e32 v116, v220
	v_mov_b32_e32 v117, v220
	v_mov_b32_e32 v118, v220
	v_mov_b32_e32 v119, v220
	v_mov_b32_e32 v120, v220
	s_waitcnt lgkmcnt(0)
	v_mfma_f32_32x32x16_bf16 v[50:65], v[6:9], v[142:145], v[50:65]
	v_mov_b32_e32 v121, v220
	v_mov_b32_e32 v122, v220
	v_mov_b32_e32 v123, v220
	v_mov_b32_e32 v124, v220
	v_mov_b32_e32 v125, v220
	v_mov_b32_e32 v126, v220
	v_mov_b32_e32 v127, v220
	v_mfma_f32_32x32x16_bf16 v[34:49], v[2:5], v[142:145], v[34:49]
	ds_read_b128 v[2:5], v219 offset:6784
	ds_read_b128 v[6:9], v219 offset:128
	v_mov_b32_e32 v128, v220
	v_mov_b32_e32 v129, v220
	s_waitcnt lgkmcnt(0)
	v_mfma_f32_32x32x16_bf16 v[50:65], v[6:9], v[146:149], v[50:65]
	v_mfma_f32_32x32x16_bf16 v[34:49], v[2:5], v[146:149], v[34:49]
	ds_read_b128 v[2:5], v219 offset:6816
	ds_read_b128 v[6:9], v219 offset:160
	s_waitcnt lgkmcnt(0)
	s_barrier
	v_mfma_f32_32x32x16_bf16 v[50:65], v[6:9], v[150:153], v[50:65]
	v_mov_b32_e32 v6, v1
	v_mov_b32_e32 v7, v1
	v_mov_b32_e32 v8, v1
	v_mov_b32_e32 v9, v1
	v_mfma_f32_32x32x16_bf16 v[34:49], v[2:5], v[150:153], v[34:49]
	v_lshl_add_u64 v[2:3], s[0:1], 0, v[18:19]
	v_readlane_b32 s0, v253, 55
	v_lshl_add_u64 v[2:3], v[20:21], 1, v[2:3]
	v_readlane_b32 s1, v253, 56
	v_mov_b32_e32 v4, v1
	v_mov_b32_e32 v5, v1
	v_lshl_add_u64 v[214:215], s[0:1], 0, v[2:3]
	v_mov_b32_e32 v2, v1
	v_mov_b32_e32 v3, v1
	v_mov_b32_e32 v18, v1
	v_mov_b32_e32 v19, v1
	v_mov_b32_e32 v20, v1
	v_mov_b32_e32 v21, v1
	v_mov_b64_e32 v[32:33], v[30:31]
	v_mov_b64_e32 v[30:31], v[28:29]
	v_mov_b64_e32 v[28:29], v[26:27]
	v_mov_b64_e32 v[26:27], v[24:25]
	v_mov_b64_e32 v[24:25], v[22:23]
	v_mov_b64_e32 v[22:23], v[20:21]
	v_mov_b64_e32 v[20:21], v[18:19]
	v_mov_b64_e32 v[18:19], v[16:17]
	v_mov_b64_e32 v[16:17], v[14:15]
	v_mov_b64_e32 v[14:15], v[12:13]
	v_mov_b64_e32 v[12:13], v[10:11]
	v_mov_b64_e32 v[10:11], v[8:9]
	v_mov_b64_e32 v[8:9], v[6:7]
	v_mov_b64_e32 v[6:7], v[4:5]
	v_mov_b64_e32 v[4:5], v[2:3]
	v_mov_b64_e32 v[2:3], v[0:1]
	s_mov_b32 s38, s36
	s_mov_b32 s39, s36
	s_mov_b32 s37, s36
	v_mov_b64_e32 v[200:201], s[38:39]
	v_mov_b64_e32 v[198:199], s[36:37]
	s_cbranch_execnz .LBB0_733

.Lnegc_keep_0:
	s_min_u32 s4, s16, 29
	s_add_i32 s6, s4, 2
	v_mad_u64_u32 v[66:67], s[0:1], v194, s6, v[206:207]
	global_load_dwordx4 v[162:165], v[66:67], off
	v_mad_u64_u32 v[66:67], s[0:1], v208, s6, v[210:211]
	global_load_dwordx4 v[158:161], v[66:67], off
	global_load_dwordx4 v[154:157], v[214:215], off
	ds_read_b128 v[66:69], v219 offset:13312
	ds_read_b128 v[174:177], v219 offset:13344
	ds_read_b128 v[86:89], v219 offset:19968
	ds_read_b128 v[186:189], v219 offset:13376
	ds_read_b128 v[178:181], v219 offset:20000
	ds_read_b128 v[182:185], v219 offset:20032
	v_max3_f32 v0, v240, v50, v51
	v_max3_f32 v70, v240, v52, v53
	s_nop 0
	v_max3_f32 v0, v0, v34, v35
	v_max3_f32 v70, v70, v36, v37
	s_waitcnt lgkmcnt(5)
	v_mfma_f32_32x32x16_bf16 v[98:113], v[66:69], v[130:133], v[114:129]
	ds_read_b128 v[94:97], v219 offset:13408
	ds_read_b128 v[82:85], v219 offset:20064
	v_max3_f32 v0, v0, v54, v55
	v_max3_f32 v70, v70, v56, v57
	s_nop 0
	v_max3_f32 v0, v0, v38, v39
	v_max3_f32 v70, v70, v40, v41
	s_nop 0
	v_max3_f32 v66, v70, v60, v61
	v_max3_f32 v0, v0, v58, v59
	s_nop 0
	v_max3_f32 v193, v66, v44, v45
	s_waitcnt lgkmcnt(5)
	v_mfma_f32_32x32x16_bf16 v[66:81], v[86:89], v[130:133], v[114:129]
	v_max3_f32 v0, v0, v42, v43
	ds_read_b128 v[90:93], v219 offset:13440
	ds_read_b128 v[86:89], v219 offset:20096
	ds_read_b64_tr_b16 v[170:171], v221 offset:26624
	ds_read_b64_tr_b16 v[172:173], v221 offset:27136
	ds_read_b64_tr_b16 v[166:167], v221 offset:30720
	ds_read_b64_tr_b16 v[168:169], v221 offset:31232
	v_mfma_f32_32x32x16_bf16 v[98:113], v[174:177], v[134:137], v[98:113]
	v_max3_f32 v0, v0, v62, v63
	v_max3_f32 v174, v193, v64, v65
	s_nop 0
	v_max3_f32 v0, v0, v46, v47
	v_max3_f32 v174, v174, v48, v49
	s_waitcnt lgkmcnt(9)
	v_mfma_f32_32x32x16_bf16 v[66:81], v[178:181], v[134:137], v[66:81]
	v_max_f32_e32 v0, v0, v174
	s_nop 0
	v_mov_b32_e32 v174, v0
	s_nop 1
	v_permlane32_swap_b32_e32 v0, v174
	v_max_f32_e32 v0, v0, v174
	s_nop 0
	v_cmp_lt_f32_e32 vcc, s2, v0
	v_cmp_gt_f32_e64 s[0:1], s3, v0
	s_or_b64 vcc, vcc, s[0:1]
	s_cmp_lg_u64 vcc, 0
	s_cselect_b64 s[14:15], -1, 0
	s_cbranch_vccz .LBB0_735
	v_cmp_lt_f32_e32 vcc, 0, v0
	s_or_b64 vcc, vcc, s[0:1]
	s_nop 0
	v_cndmask_b32_e32 v190, 0, v0, vcc
	v_exp_f32_e64 v0, -v190
	v_pk_add_f32 v[50:51], v[50:51], v[190:191] op_sel_hi:[1,0] neg_lo:[0,1] neg_hi:[0,1]
	v_pk_add_f32 v[52:53], v[52:53], v[190:191] op_sel_hi:[1,0] neg_lo:[0,1] neg_hi:[0,1]
	v_pk_add_f32 v[54:55], v[54:55], v[190:191] op_sel_hi:[1,0] neg_lo:[0,1] neg_hi:[0,1]
	v_pk_add_f32 v[56:57], v[56:57], v[190:191] op_sel_hi:[1,0] neg_lo:[0,1] neg_hi:[0,1]
	v_pk_add_f32 v[58:59], v[58:59], v[190:191] op_sel_hi:[1,0] neg_lo:[0,1] neg_hi:[0,1]
	v_pk_add_f32 v[60:61], v[60:61], v[190:191] op_sel_hi:[1,0] neg_lo:[0,1] neg_hi:[0,1]
	v_pk_add_f32 v[62:63], v[62:63], v[190:191] op_sel_hi:[1,0] neg_lo:[0,1] neg_hi:[0,1]
	v_pk_add_f32 v[64:65], v[64:65], v[190:191] op_sel_hi:[1,0] neg_lo:[0,1] neg_hi:[0,1]
	v_sub_f32_e32 v49, v49, v190
	v_sub_f32_e32 v48, v48, v190
	v_sub_f32_e32 v47, v47, v190
	v_sub_f32_e32 v46, v46, v190
	v_sub_f32_e32 v45, v45, v190
	v_sub_f32_e32 v44, v44, v190
	v_sub_f32_e32 v43, v43, v190
	v_sub_f32_e32 v42, v42, v190
	v_sub_f32_e32 v41, v41, v190
	v_sub_f32_e32 v40, v40, v190
	v_sub_f32_e32 v39, v39, v190
	v_sub_f32_e32 v38, v38, v190
	v_sub_f32_e32 v37, v37, v190
	v_sub_f32_e32 v36, v36, v190
	v_sub_f32_e32 v35, v35, v190
	v_sub_f32_e32 v34, v34, v190
	v_add_f32_e32 v220, v220, v190
	s_branch .LBB0_736

.LBB0_738:
	v_cvt_pk_bf16_f32 v50, v50, v51
	v_cvt_pk_bf16_f32 v51, v52, v53
	v_cvt_pk_bf16_f32 v52, v54, v182
	v_cvt_pk_bf16_f32 v53, v56, v183
	v_cvt_pk_bf16_f32 v54, v55, v57
	v_cvt_pk_bf16_f32 v55, v58, v59
	v_mfma_f32_32x32x16_bf16 v[82:97], v[198:201], v[50:53], 0
	v_cvt_pk_bf16_f32 v56, v60, v61
	v_cvt_pk_bf16_f32 v57, v62, v63
	v_mfma_f32_32x32x16_bf16 v[2:17], v[170:173], v[50:53], v[2:17]
	ds_read_b64_tr_b16 v[58:59], v221 offset:28672
	ds_read_b64_tr_b16 v[60:61], v221 offset:29184
	v_exp_f32_e32 v62, v34
	v_exp_f32_e32 v63, v35
	v_exp_f32_e32 v64, v36
	v_exp_f32_e32 v65, v37
	v_mfma_f32_32x32x16_bf16 v[18:33], v[166:169], v[50:53], v[18:33]
	ds_read_b64_tr_b16 v[34:35], v221 offset:32768
	ds_read_b64_tr_b16 v[36:37], v221 offset:33280
	v_exp_f32_e32 v50, v38
	v_exp_f32_e32 v51, v39
	v_exp_f32_e32 v52, v40
	v_exp_f32_e32 v41, v41
	v_mfma_f32_32x32x16_bf16 v[82:97], v[198:201], v[54:57], v[82:97]
	v_cvt_pk_bf16_f32 v38, v62, v63
	v_cvt_pk_bf16_f32 v39, v64, v65
	v_cvt_pk_bf16_f32 v40, v50, v51
	v_cvt_pk_bf16_f32 v41, v52, v41
	s_waitcnt lgkmcnt(6)
	v_mfma_f32_32x32x16_bf16 v[2:17], v[178:181], v[54:57], v[2:17]
	ds_read_b64_tr_b16 v[50:51], v221 offset:29696
	ds_read_b64_tr_b16 v[52:53], v221 offset:30208
	v_exp_f32_e32 v62, v42
	v_exp_f32_e32 v63, v43
	v_exp_f32_e32 v64, v44
	v_exp_f32_e32 v65, v45
	s_waitcnt lgkmcnt(6)
	v_mfma_f32_32x32x16_bf16 v[18:33], v[174:177], v[54:57], v[18:33]
	ds_read_b64_tr_b16 v[42:43], v221 offset:33792
	ds_read_b64_tr_b16 v[44:45], v221 offset:34304
	v_exp_f32_e32 v54, v46
	v_exp_f32_e32 v55, v47
	v_exp_f32_e32 v56, v48
	v_exp_f32_e32 v49, v49
	v_mfma_f32_32x32x16_bf16 v[82:97], v[198:201], v[38:41], v[82:97]
	v_cvt_pk_bf16_f32 v46, v62, v63
	v_cvt_pk_bf16_f32 v47, v64, v65
	v_cvt_pk_bf16_f32 v48, v54, v55
	v_cvt_pk_bf16_f32 v49, v56, v49
	s_waitcnt lgkmcnt(6)
	v_mfma_f32_32x32x16_bf16 v[2:17], v[58:61], v[38:41], v[2:17]
	s_waitcnt lgkmcnt(4)
	v_mfma_f32_32x32x16_bf16 v[18:33], v[34:37], v[38:41], v[18:33]
	v_mfma_f32_32x32x16_bf16 v[82:97], v[198:201], v[46:49], v[82:97]
	s_waitcnt lgkmcnt(2)
	v_mfma_f32_32x32x16_bf16 v[2:17], v[50:53], v[46:49], v[2:17]
	s_waitcnt lgkmcnt(0)
	v_mfma_f32_32x32x16_bf16 v[18:33], v[42:45], v[46:49], v[18:33]
	s_and_saveexec_b64 s[0:1], s[44:45]
	s_cbranch_execz .LBB0_740
	s_waitcnt vmcnt(2)
	ds_write_b128 v195, v[162:165]

.Lnegc_keep_1:
	s_min_u32 s0, s16, 28
	s_add_i32 s6, s0, 3
	v_mad_u64_u32 v[34:35], s[0:1], v194, s6, v[206:207]
	global_load_dwordx4 v[162:165], v[34:35], off
	v_mad_u64_u32 v[34:35], s[0:1], v208, s6, v[210:211]
	s_lshl_b32 s40, s4, 18
	global_load_dwordx4 v[158:161], v[34:35], off
	v_lshl_add_u64 v[34:35], v[212:213], 0, s[40:41]
	s_mov_b32 s0, 0x80000
	v_add_co_u32_e32 v34, vcc, s0, v34
	v_max3_f32 v38, v240, v98, v99
	v_max3_f32 v39, v240, v100, v101
	s_nop 1
	v_addc_co_u32_e32 v35, vcc, 0, v35, vcc
	global_load_dwordx4 v[154:157], v[34:35], off offset:128
	ds_read_b128 v[34:37], v219
	ds_read_b128 v[174:177], v219 offset:32
	ds_read_b128 v[88:91], v219 offset:6656
	ds_read_b128 v[190:193], v219 offset:64
	ds_read_b128 v[178:181], v219 offset:6688
	ds_read_b128 v[186:189], v219 offset:6720
	v_max3_f32 v38, v38, v66, v67
	v_max3_f32 v39, v39, v68, v69
	s_waitcnt lgkmcnt(5)
	v_mfma_f32_32x32x16_bf16 v[50:65], v[34:37], v[130:133], v[114:129]
	ds_read_b128 v[182:185], v219 offset:96
	ds_read_b128 v[84:87], v219 offset:6752
	v_max3_f32 v38, v38, v102, v103
	v_max3_f32 v39, v39, v104, v105
	s_nop 0
	v_max3_f32 v38, v38, v70, v71
	v_max3_f32 v39, v39, v72, v73
	s_nop 0
	v_max3_f32 v34, v38, v106, v107
	v_max3_f32 v35, v39, v108, v109
	s_nop 0
	v_max3_f32 v96, v34, v74, v75
	v_max3_f32 v97, v35, v76, v77
	s_waitcnt lgkmcnt(5)
	v_mfma_f32_32x32x16_bf16 v[34:49], v[88:91], v[130:133], v[114:129]
	ds_read_b128 v[92:95], v219 offset:128
	ds_read_b128 v[88:91], v219 offset:6784
	ds_read_b64_tr_b16 v[170:171], v221 offset:34816
	ds_read_b64_tr_b16 v[172:173], v221 offset:35328
	ds_read_b64_tr_b16 v[166:167], v221 offset:38912
	ds_read_b64_tr_b16 v[168:169], v221 offset:39424
	v_mfma_f32_32x32x16_bf16 v[50:65], v[174:177], v[134:137], v[50:65]
	v_max3_f32 v96, v96, v110, v111
	v_max3_f32 v97, v97, v112, v113
	s_nop 0
	v_max3_f32 v96, v96, v78, v79
	v_max3_f32 v97, v97, v80, v81
	s_waitcnt lgkmcnt(9)
	v_mfma_f32_32x32x16_bf16 v[34:49], v[178:181], v[134:137], v[34:49]
	v_max_f32_e32 v96, v96, v97
	s_nop 0
	v_mov_b32_e32 v97, v96
	s_nop 1
	v_permlane32_swap_b32_e32 v96, v97
	v_max_f32_e32 v96, v96, v97
	s_nop 0
	v_cmp_lt_f32_e32 vcc, s2, v96
	v_cmp_gt_f32_e64 s[0:1], s3, v96
	s_or_b64 vcc, vcc, s[0:1]
	s_cmp_lg_u64 vcc, 0
	s_cselect_b64 s[14:15], -1, 0
	s_cbranch_vccz .LBB0_746
	v_cmp_lt_f32_e32 vcc, 0, v96
	s_or_b64 vcc, vcc, s[0:1]
	s_nop 0
	v_cndmask_b32_e32 v216, 0, v96, vcc
	v_exp_f32_e64 v218, -v216
	v_pk_add_f32 v[98:99], v[98:99], v[216:217] op_sel_hi:[1,0] neg_lo:[0,1] neg_hi:[0,1]
	v_pk_add_f32 v[100:101], v[100:101], v[216:217] op_sel_hi:[1,0] neg_lo:[0,1] neg_hi:[0,1]
	v_pk_add_f32 v[102:103], v[102:103], v[216:217] op_sel_hi:[1,0] neg_lo:[0,1] neg_hi:[0,1]
	v_pk_add_f32 v[104:105], v[104:105], v[216:217] op_sel_hi:[1,0] neg_lo:[0,1] neg_hi:[0,1]
	v_pk_add_f32 v[106:107], v[106:107], v[216:217] op_sel_hi:[1,0] neg_lo:[0,1] neg_hi:[0,1]
	v_pk_add_f32 v[108:109], v[108:109], v[216:217] op_sel_hi:[1,0] neg_lo:[0,1] neg_hi:[0,1]
	v_pk_add_f32 v[110:111], v[110:111], v[216:217] op_sel_hi:[1,0] neg_lo:[0,1] neg_hi:[0,1]
	v_pk_add_f32 v[112:113], v[112:113], v[216:217] op_sel_hi:[1,0] neg_lo:[0,1] neg_hi:[0,1]
	v_sub_f32_e32 v81, v81, v216
	v_sub_f32_e32 v80, v80, v216
	v_sub_f32_e32 v79, v79, v216
	v_sub_f32_e32 v78, v78, v216
	v_sub_f32_e32 v77, v77, v216
	v_sub_f32_e32 v76, v76, v216
	v_sub_f32_e32 v75, v75, v216
	v_sub_f32_e32 v74, v74, v216
	v_sub_f32_e32 v73, v73, v216
	v_sub_f32_e32 v72, v72, v216
	v_sub_f32_e32 v71, v71, v216
	v_sub_f32_e32 v70, v70, v216
	v_sub_f32_e32 v69, v69, v216
	v_sub_f32_e32 v68, v68, v216
	v_sub_f32_e32 v67, v67, v216
	v_sub_f32_e32 v66, v66, v216
	v_add_f32_e32 v220, v220, v216
	s_branch .LBB0_747

.LBB0_749:
	v_cvt_pk_bf16_f32 v108, v96, v97
	v_cvt_pk_bf16_f32 v109, v98, v99
	v_cvt_pk_bf16_f32 v110, v100, v102
	v_cvt_pk_bf16_f32 v111, v103, v186
	v_cvt_pk_bf16_f32 v102, v84, v85
	v_cvt_pk_bf16_f32 v103, v86, v87
	v_mfma_f32_32x32x16_bf16 v[84:99], v[198:201], v[108:111], 0
	v_cvt_pk_bf16_f32 v100, v101, v104
	v_cvt_pk_bf16_f32 v101, v105, v106
	v_mfma_f32_32x32x16_bf16 v[2:17], v[170:173], v[108:111], v[2:17]
	ds_read_b64_tr_b16 v[104:105], v221 offset:36864
	ds_read_b64_tr_b16 v[106:107], v221 offset:37376
	v_exp_f32_e32 v112, v66
	v_exp_f32_e32 v113, v67
	v_exp_f32_e32 v170, v68
	v_exp_f32_e32 v171, v69
	v_mfma_f32_32x32x16_bf16 v[18:33], v[166:169], v[108:111], v[18:33]
	ds_read_b64_tr_b16 v[66:67], v221 offset:40960
	ds_read_b64_tr_b16 v[68:69], v221 offset:41472
	v_exp_f32_e32 v108, v70
	v_exp_f32_e32 v109, v71
	v_exp_f32_e32 v110, v72
	v_exp_f32_e32 v73, v73
	v_mfma_f32_32x32x16_bf16 v[84:99], v[198:201], v[100:103], v[84:99]
	v_cvt_pk_bf16_f32 v70, v112, v113
	v_cvt_pk_bf16_f32 v71, v170, v171
	v_cvt_pk_bf16_f32 v72, v108, v109
	v_cvt_pk_bf16_f32 v73, v110, v73
	s_waitcnt lgkmcnt(6)
	v_mfma_f32_32x32x16_bf16 v[2:17], v[178:181], v[100:103], v[2:17]
	ds_read_b64_tr_b16 v[108:109], v221 offset:37888
	ds_read_b64_tr_b16 v[110:111], v221 offset:38400
	v_exp_f32_e32 v112, v74
	v_exp_f32_e32 v113, v75
	v_exp_f32_e32 v166, v76
	v_exp_f32_e32 v167, v77
	s_waitcnt lgkmcnt(6)
	v_mfma_f32_32x32x16_bf16 v[18:33], v[174:177], v[100:103], v[18:33]
	ds_read_b64_tr_b16 v[74:75], v221 offset:41984
	ds_read_b64_tr_b16 v[76:77], v221 offset:42496
	v_exp_f32_e32 v100, v78
	v_exp_f32_e32 v101, v79
	v_exp_f32_e32 v102, v80
	v_exp_f32_e32 v81, v81
	v_mfma_f32_32x32x16_bf16 v[84:99], v[198:201], v[70:73], v[84:99]
	v_cvt_pk_bf16_f32 v78, v112, v113
	v_cvt_pk_bf16_f32 v79, v166, v167
	v_cvt_pk_bf16_f32 v80, v100, v101
	v_cvt_pk_bf16_f32 v81, v102, v81
	s_waitcnt lgkmcnt(6)
	v_mfma_f32_32x32x16_bf16 v[2:17], v[104:107], v[70:73], v[2:17]
	s_waitcnt lgkmcnt(4)
	v_mfma_f32_32x32x16_bf16 v[18:33], v[66:69], v[70:73], v[18:33]
	v_mfma_f32_32x32x16_bf16 v[84:99], v[198:201], v[78:81], v[84:99]
	s_waitcnt lgkmcnt(2)
	v_mfma_f32_32x32x16_bf16 v[2:17], v[108:111], v[78:81], v[2:17]
	s_waitcnt lgkmcnt(0)
	v_mfma_f32_32x32x16_bf16 v[18:33], v[74:77], v[78:81], v[18:33]
	s_and_saveexec_b64 s[0:1], s[44:45]
	s_cbranch_execz .LBB0_751
	s_waitcnt vmcnt(2)
	ds_write_b128 v195, v[162:165] offset:13312

; #define LAS __attribute__((address_space(3)))
; #define FA_LOADK(kt) do { _Pragma("unroll") for (int i_ = 0; i_ < NKI; ++i_) kreg[i_] = *(const u32x4*)(ksrc[i_] + (size_t)(unsigned)(kt) * kstep[i_]); } while (0)
; #define FA_LOADV(kt) do { _Pragma("unroll") for (int i_ = 0; i_ < NVI; ++i_) vreg[i_] = *(const u32x4*)(vsrc0 + (size_t)(unsigned)(kt) * vstep + (size_t)i_ * vrowoff); } while (0)
; #define FA_STOREK(buf) do { _Pragma("unroll") for (int i_ = 0; i_ < NKI; ++i_) { if (kval[i_]) *(LAS u32x4*)(Kl + (buf) * KBUF + kdst[i_]) = kreg[i_]; } } while (0)
; #define FA_STOREV(buf) do { _Pragma("unroll") for (int i_ = 0; i_ < NVI; ++i_) *(LAS u32x4*)(Vl + (buf) * VBUF + vdst0 + i_ * VDSTOFF) = vreg[i_]; } while (0)
;     ...
;     f32x16 zero16;
; #pragma unroll
;     for (int r = 0; r < 16; ++r) zero16[r] = 0.f;
;     f32x16 pA0 = zero16, pA1 = zero16, pB0 = zero16, pB1 = zero16;
;     constexpr bool VPRE = (DV <= 64); constexpr int KD = (DV <= 64) ? 3 : 2;
;     constexpr bool NEGM = (MODE != 1);
;     f32x16 negc = zero16; float cbs = 0.f, pend = 0.f; bool pendf = false;
;     if (NEGM) mrun = 0.f;
;     if (!RES) {
;         u32x4 k2_[NKI];
;         FA_LOADK(kt_lo); FA_LOADV(kt_lo);
; #pragma unroll
;         for (int i_ = 0; i_ < NKI; ++i_) k2_[i_] = *(const u32x4*)(ksrc[i_] + (size_t)(unsigned)(kt_lo + 1) * kstep[i_]);
;         FA_STOREK(0); FA_STOREV(0);
; #pragma unroll
;         for (int i_ = 0; i_ < NKI; ++i_) { if (kval[i_]) *(LAS u32x4*)(Kl + KBUF + kdst[i_]) = k2_[i_]; }
;         __syncthreads();
;         if (NEGM) { if (MODE == 2) {     const int tl0 = 64 * kt_lo; float c0_ = 0.f; if (tl0 + 63 - qw0 <= -128) c0_ = lut[0]; else if (tl0 - (qw0 + 31) >= 128) c0_ = lut[511]; cbs = c0_;
; #pragma unroll
;         for (int r_ = 0; r_ < 16; ++r_) negc[r_] = c0_; } }
;         FA_QK(pA0, pA1, 0, negc);
;         __syncthreads();
;     } else {
;         FA_QK(pA0, pA1, kt_lo - win_lo, zero16);
;     }
.LBB0_919:
	v_and_b32_e32 v21, 31, v19
	s_movk_i32 s0, 0x90
	v_mad_u32_u24 v2, v21, s0, 0
	v_add_u32_e32 v215, v2, v0
	ds_read_b128 v[2:5], v215
	ds_read_b128 v[6:9], v215 offset:32
	s_waitcnt lgkmcnt(2)
	v_mov_b32_e32 v113, v112
	v_mov_b32_e32 v114, v112
	v_mov_b32_e32 v115, v112
	v_mov_b32_e32 v116, v112
	v_mov_b32_e32 v117, v112
	v_mov_b32_e32 v118, v112
	v_mov_b32_e32 v119, v112
	v_mov_b32_e32 v120, v112
	v_mov_b32_e32 v121, v112
	v_mov_b32_e32 v122, v112
	v_mov_b32_e32 v123, v112
	v_mov_b32_e32 v124, v112
	v_mov_b32_e32 v125, v112
	v_mov_b32_e32 v126, v112
	v_mov_b32_e32 v127, v112
	v_mov_b64_e32 v[80:81], v[112:113]
	v_mov_b64_e32 v[82:83], v[114:115]
	s_waitcnt lgkmcnt(1)
	v_mfma_f32_32x32x16_bf16 v[128:143], v[2:5], v[176:179], v[112:127]
	ds_read_b128 v[2:5], v215 offset:4608
	v_mov_b64_e32 v[84:85], v[116:117]
	v_mov_b64_e32 v[86:87], v[118:119]
	v_mov_b64_e32 v[88:89], v[120:121]
	v_mov_b64_e32 v[90:91], v[122:123]
	v_mov_b64_e32 v[92:93], v[124:125]
	v_mov_b64_e32 v[94:95], v[126:127]
	s_waitcnt vmcnt(0)
	ds_read_b128 v[10:13], v215 offset:4640
	s_waitcnt lgkmcnt(2)
	v_mfma_f32_32x32x16_bf16 v[128:143], v[6:9], v[180:183], v[128:143]
	v_lshlrev_b32_e32 v6, 1, v19
	v_mad_i64_i32 v[16:17], s[0:1], v20, s7, 0
	v_and_b32_e32 v20, 32, v6
	v_lshlrev_b32_e32 v6, 3, v19
	v_and_b32_e32 v22, 24, v6
	v_lshlrev_b32_e32 v19, 4, v19
	s_waitcnt lgkmcnt(1)
	v_mfma_f32_32x32x16_bf16 v[80:95], v[2:5], v[176:179], v[80:95]
	ds_read_b128 v[2:5], v215 offset:64
	s_and_b32 s29, s23, 0x700
	s_and_b32 s0, s4, 7
	s_add_i32 s4, s29, s6
	s_lshl_b32 s25, s10, 7
	s_lshl_b32 s30, s0, 8
	s_sub_i32 s31, 0xbf, s4
	s_waitcnt lgkmcnt(1)
	v_mfma_f32_32x32x16_bf16 v[80:95], v[10:13], v[180:183], v[80:95]
	ds_read_b128 v[6:9], v215 offset:4672
	ds_read_b128 v[10:13], v215 offset:96
	s_add_u32 s0, s30, s27
	s_addc_u32 s1, 0, s26
	s_mov_b64 s[20:21], 0
	v_mov_b32_e32 v217, 0
	v_mov_b32_e32 v160, v112
	v_mov_b32_e32 v161, v112
	s_waitcnt lgkmcnt(2)
	v_mfma_f32_32x32x16_bf16 v[128:143], v[2:5], v[184:187], v[128:143]
	v_and_b32_e32 v2, 0xc0, v19
	v_lshl_or_b32 v2, v18, 8, v2
	v_or3_b32 v18, v2, v20, v22
	ds_read_b128 v[2:5], v215 offset:4704
	v_add_u32_e32 v113, 0, v18
	v_mov_b32_e32 v162, v112
	v_mov_b32_e32 v163, v112
	s_waitcnt lgkmcnt(2)
	v_mfma_f32_32x32x16_bf16 v[80:95], v[6:9], v[184:187], v[80:95]
	v_lshl_add_u64 v[6:7], s[0:1], 0, v[16:17]
	v_readlane_b32 s0, v254, 1
	v_lshl_add_u64 v[6:7], v[14:15], 1, v[6:7]
	v_readlane_b32 s1, v254, 2
	v_mov_b32_e32 v14, v1
	v_mov_b32_e32 v15, v1
	v_lshl_add_u64 v[212:213], s[0:1], 0, v[6:7]
	s_waitcnt lgkmcnt(1)
	v_mfma_f32_32x32x16_bf16 v[128:143], v[10:13], v[188:191], v[128:143]
	v_add_lshl_u32 v6, s4, v21, 2
	v_sub_u32_e32 v0, v0, v6
	v_readlane_b32 s0, v254, 5
	v_mov_b32_e32 v6, v1
	v_mov_b32_e32 v7, v1
	v_add_u32_e32 v216, s0, v0
	v_mov_b32_e32 v0, v1
	s_waitcnt lgkmcnt(0)
	v_mfma_f32_32x32x16_bf16 v[80:95], v[2:5], v[188:191], v[80:95]
	v_mov_b32_e32 v2, v1
	v_mov_b32_e32 v3, v1
	v_mov_b32_e32 v4, v1
	v_mov_b32_e32 v5, v1
	v_mov_b32_e32 v8, v1
	v_mov_b32_e32 v9, v1
	v_mov_b32_e32 v10, v1
	v_mov_b32_e32 v11, v1
	v_mov_b32_e32 v12, v1
	v_mov_b32_e32 v13, v1
	v_mov_b64_e32 v[30:31], v[14:15]
	v_mov_b64_e32 v[46:47], v[14:15]
	v_mov_b64_e32 v[62:63], v[14:15]
	v_mov_b64_e32 v[78:79], v[14:15]
	s_mov_b32 s4, -2
	v_mov_b64_e32 v[28:29], v[12:13]
	v_mov_b64_e32 v[26:27], v[10:11]
	v_mov_b64_e32 v[24:25], v[8:9]
	v_mov_b64_e32 v[22:23], v[6:7]
	v_mov_b64_e32 v[20:21], v[4:5]
	v_mov_b64_e32 v[18:19], v[2:3]
	v_mov_b64_e32 v[16:17], v[0:1]
	v_mov_b64_e32 v[44:45], v[12:13]
	v_mov_b64_e32 v[42:43], v[10:11]
	v_mov_b64_e32 v[40:41], v[8:9]
	v_mov_b64_e32 v[38:39], v[6:7]
	v_mov_b64_e32 v[36:37], v[4:5]
	v_mov_b64_e32 v[34:35], v[2:3]
	v_mov_b64_e32 v[32:33], v[0:1]
	v_mov_b64_e32 v[60:61], v[12:13]
	v_mov_b64_e32 v[58:59], v[10:11]
	v_mov_b64_e32 v[56:57], v[8:9]
	v_mov_b64_e32 v[54:55], v[6:7]
	v_mov_b64_e32 v[52:53], v[4:5]
	v_mov_b64_e32 v[50:51], v[2:3]
	v_mov_b64_e32 v[48:49], v[0:1]
	v_mov_b64_e32 v[76:77], v[12:13]
	v_mov_b64_e32 v[74:75], v[10:11]
	v_mov_b64_e32 v[72:73], v[8:9]
	v_mov_b64_e32 v[70:71], v[6:7]
	v_mov_b64_e32 v[68:69], v[4:5]
	v_mov_b64_e32 v[66:67], v[2:3]
	v_mov_b64_e32 v[64:65], v[0:1]
	v_mov_b32_e32 v15, 0
	v_mov_b32_e32 v0, 0
	v_mov_b32_e32 v164, v112
	v_mov_b32_e32 v165, v112
	v_mov_b32_e32 v166, v112
	v_mov_b32_e32 v167, v112
	v_mov_b32_e32 v168, v112
	v_mov_b32_e32 v169, v112
	v_mov_b32_e32 v170, v112
	v_mov_b32_e32 v171, v112
	v_mov_b32_e32 v172, v112
	v_mov_b32_e32 v173, v112
	v_mov_b32_e32 v174, v112
	v_mov_b32_e32 v175, v112
	s_barrier
	ds_read_b32 v0, v1 offset:61440
	s_waitcnt lgkmcnt(0)
	v_readfirstlane_b32 s100, v0
	ds_read_b32 v0, v1 offset:63484
	s_waitcnt lgkmcnt(0)
	v_readfirstlane_b32 s101, v0
	v_mov_b32_e32 v0, 0
	s_add_i32 s0, s31, 0xfffffea2
	s_cmp_lt_u32 s0, 0xfffffea3
	s_cbranch_scc0 .LBB0_925

.LBB0_922:
	s_add_i32 s0, s31, 0xffffff81
	s_cmpk_lt_i32 s0, 0x9f
	v_mov_b32_e32 v0, 0
	s_cbranch_scc1 .LBB0_924
	v_mov_b32_e32 v0, s101

.LBB0_927:
.LBB0_928:
	s_waitcnt lgkmcnt(0)
	v_mov_b32_e32 v0, s100

.Lnegc_keep_2:
	s_min_u32 s0, s34, 29
	s_add_i32 s0, s0, 2
	v_mul_u32_u24_e32 v0, s0, v206
	v_add_co_u32_e32 v10, vcc, s93, v212
	v_lshl_add_u64 v[2:3], v[208:209], 0, v[0:1]
	s_nop 0
	v_addc_co_u32_e32 v11, vcc, 0, v213, vcc
	global_load_dwordx4 v[2:5], v[2:3], off
	s_nop 0
	global_load_dwordx4 v[6:9], v[212:213], off
	s_nop 0
	global_load_dwordx4 v[10:13], v[10:11], off
	ds_read_b128 v[96:99], v215 offset:9216
	ds_read_b128 v[220:223], v215 offset:9248
	ds_read_b128 v[114:117], v215 offset:13824
	ds_read_b128 v[224:227], v215 offset:13856
	v_max3_f32 v0, v240, v128, v129
	v_max3_f32 v14, v240, v130, v131
	s_nop 0
	v_max3_f32 v0, v0, v80, v81
	v_max3_f32 v14, v14, v82, v83
	s_waitcnt lgkmcnt(3)
	v_mfma_f32_32x32x16_bf16 v[144:159], v[96:99], v[176:179], v[160:175]
	ds_read_b128 v[192:195], v215 offset:9280
	ds_read_b128 v[118:121], v215 offset:13888
	v_max3_f32 v0, v0, v132, v133
	v_max3_f32 v14, v14, v134, v135
	s_nop 0
	v_max3_f32 v0, v0, v84, v85
	v_max3_f32 v14, v14, v86, v87
	s_waitcnt lgkmcnt(3)
	v_mfma_f32_32x32x16_bf16 v[96:111], v[114:117], v[176:179], v[160:175]
	v_max3_f32 v0, v0, v136, v137
	v_max3_f32 v14, v14, v138, v139
	s_nop 0
	v_max3_f32 v0, v0, v88, v89
	v_max3_f32 v14, v14, v90, v91
	v_mfma_f32_32x32x16_bf16 v[144:159], v[220:223], v[180:183], v[144:159]
	ds_read_b128 v[122:125], v215 offset:9312
	ds_read_b128 v[114:117], v215 offset:13920
	v_max3_f32 v0, v0, v140, v141
	v_max3_f32 v14, v14, v142, v143
	s_nop 0
	v_max3_f32 v0, v0, v92, v93
	v_max3_f32 v14, v14, v94, v95
	s_waitcnt lgkmcnt(4)
	v_mfma_f32_32x32x16_bf16 v[96:111], v[224:227], v[180:183], v[96:111]
	v_max_f32_e32 v0, v0, v14
	s_nop 0
	v_mov_b32_e32 v14, v0
	s_nop 1
	v_permlane32_swap_b32_e32 v0, v14
	v_max_f32_e32 v0, v0, v14
	s_nop 0
	v_cmp_lt_f32_e32 vcc, s2, v0
	v_cmp_gt_f32_e64 s[0:1], s3, v0
	s_or_b64 vcc, vcc, s[0:1]
	s_cmp_lg_u64 vcc, 0
	s_cselect_b64 s[20:21], -1, 0
	s_cbranch_vccz .LBB0_931
	v_cmp_lt_f32_e32 vcc, 0, v0
	s_or_b64 vcc, vcc, s[0:1]
	s_nop 0
	v_cndmask_b32_e32 v0, 0, v0, vcc
	v_exp_f32_e64 v14, -v0
	v_pk_add_f32 v[128:129], v[128:129], v[0:1] op_sel_hi:[1,0] neg_lo:[0,1] neg_hi:[0,1]
	v_pk_add_f32 v[130:131], v[130:131], v[0:1] op_sel_hi:[1,0] neg_lo:[0,1] neg_hi:[0,1]
	v_pk_add_f32 v[132:133], v[132:133], v[0:1] op_sel_hi:[1,0] neg_lo:[0,1] neg_hi:[0,1]
	v_pk_add_f32 v[134:135], v[134:135], v[0:1] op_sel_hi:[1,0] neg_lo:[0,1] neg_hi:[0,1]
	v_pk_add_f32 v[136:137], v[136:137], v[0:1] op_sel_hi:[1,0] neg_lo:[0,1] neg_hi:[0,1]
	v_pk_add_f32 v[138:139], v[138:139], v[0:1] op_sel_hi:[1,0] neg_lo:[0,1] neg_hi:[0,1]
	v_pk_add_f32 v[140:141], v[140:141], v[0:1] op_sel_hi:[1,0] neg_lo:[0,1] neg_hi:[0,1]
	v_pk_add_f32 v[142:143], v[142:143], v[0:1] op_sel_hi:[1,0] neg_lo:[0,1] neg_hi:[0,1]
	v_sub_f32_e32 v95, v95, v0
	v_sub_f32_e32 v94, v94, v0
	v_sub_f32_e32 v93, v93, v0
	v_sub_f32_e32 v92, v92, v0
	v_sub_f32_e32 v91, v91, v0
	v_sub_f32_e32 v90, v90, v0
	v_sub_f32_e32 v89, v89, v0
	v_sub_f32_e32 v88, v88, v0
	v_sub_f32_e32 v87, v87, v0
	v_sub_f32_e32 v86, v86, v0
	v_sub_f32_e32 v85, v85, v0
	v_sub_f32_e32 v84, v84, v0
	v_sub_f32_e32 v83, v83, v0
	v_sub_f32_e32 v82, v82, v0
	v_sub_f32_e32 v81, v81, v0
	v_sub_f32_e32 v80, v80, v0
	v_add_f32_e32 v217, v217, v0
	s_branch .LBB0_932

.LBB0_940:
	s_cmpk_gt_i32 s31, 0xff80
	s_cbranch_scc0 .LBB0_944
	s_sub_i32 s0, s31, 63
	s_cmpk_lt_i32 s0, 0x9f
	v_mov_b32_e32 v0, 0
	s_cbranch_scc1 .LBB0_943
	v_mov_b32_e32 v0, s101

.Lnegc_keep_3:
	s_min_u32 s0, s0, 31
	s_min_u32 s1, s34, 28
	s_mul_i32 s40, s0, 0x108000
	s_add_i32 s1, s1, 3
	v_lshl_add_u64 v[6:7], v[210:211], 0, s[40:41]
	v_mul_u32_u24_e32 v0, s1, v206
	v_add_co_u32_e32 v10, vcc, s93, v6
	v_lshl_add_u64 v[2:3], v[208:209], 0, v[0:1]
	s_nop 0
	v_addc_co_u32_e32 v11, vcc, 0, v7, vcc
	global_load_dwordx4 v[2:5], v[2:3], off
	s_nop 0
	global_load_dwordx4 v[6:9], v[6:7], off
	s_nop 0
	global_load_dwordx4 v[10:13], v[10:11], off
	ds_read_b128 v[80:83], v215
	ds_read_b128 v[196:199], v215 offset:32
	ds_read_b128 v[116:119], v215 offset:4608
	ds_read_b128 v[200:203], v215 offset:4640
	v_max3_f32 v0, v240, v144, v145
	v_max3_f32 v84, v240, v146, v147
	s_nop 0
	v_max3_f32 v0, v0, v96, v97
	v_max3_f32 v84, v84, v98, v99
	s_waitcnt lgkmcnt(3)
	v_mfma_f32_32x32x16_bf16 v[128:143], v[80:83], v[176:179], v[160:175]
	ds_read_b128 v[192:195], v215 offset:64
	ds_read_b128 v[120:123], v215 offset:4672
	v_max3_f32 v0, v0, v148, v149
	v_max3_f32 v84, v84, v150, v151
	s_nop 0
	v_max3_f32 v0, v0, v100, v101
	v_max3_f32 v84, v84, v102, v103
	s_nop 0
	v_max3_f32 v80, v84, v154, v155
	v_max3_f32 v0, v0, v152, v153
	s_nop 0
	v_max3_f32 v112, v80, v106, v107
	s_waitcnt lgkmcnt(3)
	v_mfma_f32_32x32x16_bf16 v[80:95], v[116:119], v[176:179], v[160:175]
	v_max3_f32 v0, v0, v104, v105
	v_mfma_f32_32x32x16_bf16 v[128:143], v[196:199], v[180:183], v[128:143]
	ds_read_b128 v[124:127], v215 offset:96
	ds_read_b128 v[116:119], v215 offset:4704
	v_max3_f32 v0, v0, v156, v157
	v_max3_f32 v112, v112, v158, v159
	s_nop 0
	v_max3_f32 v0, v0, v108, v109
	v_max3_f32 v112, v112, v110, v111
	s_waitcnt lgkmcnt(4)
	v_mfma_f32_32x32x16_bf16 v[80:95], v[200:203], v[180:183], v[80:95]
	v_max_f32_e32 v0, v0, v112
	s_nop 0
	v_mov_b32_e32 v112, v0
	s_nop 1
	v_permlane32_swap_b32_e32 v0, v112
	v_max_f32_e32 v0, v0, v112
	s_nop 0
	v_cmp_lt_f32_e32 vcc, s2, v0
	v_cmp_gt_f32_e64 s[0:1], s3, v0
	s_or_b64 vcc, vcc, s[0:1]
	s_cmp_lg_u64 vcc, 0
	s_cselect_b64 s[20:21], -1, 0
	s_cbranch_vccz .LBB0_948
	v_cmp_lt_f32_e32 vcc, 0, v0
	s_or_b64 vcc, vcc, s[0:1]
	s_nop 0
	v_cndmask_b32_e32 v0, 0, v0, vcc
	v_exp_f32_e64 v112, -v0
	v_pk_add_f32 v[144:145], v[144:145], v[0:1] op_sel_hi:[1,0] neg_lo:[0,1] neg_hi:[0,1]
	v_pk_add_f32 v[146:147], v[146:147], v[0:1] op_sel_hi:[1,0] neg_lo:[0,1] neg_hi:[0,1]
	v_pk_add_f32 v[148:149], v[148:149], v[0:1] op_sel_hi:[1,0] neg_lo:[0,1] neg_hi:[0,1]
	v_pk_add_f32 v[150:151], v[150:151], v[0:1] op_sel_hi:[1,0] neg_lo:[0,1] neg_hi:[0,1]
	v_pk_add_f32 v[152:153], v[152:153], v[0:1] op_sel_hi:[1,0] neg_lo:[0,1] neg_hi:[0,1]
	v_pk_add_f32 v[154:155], v[154:155], v[0:1] op_sel_hi:[1,0] neg_lo:[0,1] neg_hi:[0,1]
	v_pk_add_f32 v[156:157], v[156:157], v[0:1] op_sel_hi:[1,0] neg_lo:[0,1] neg_hi:[0,1]
	v_pk_add_f32 v[158:159], v[158:159], v[0:1] op_sel_hi:[1,0] neg_lo:[0,1] neg_hi:[0,1]
	v_sub_f32_e32 v111, v111, v0
	v_sub_f32_e32 v110, v110, v0
	v_sub_f32_e32 v109, v109, v0
	v_sub_f32_e32 v108, v108, v0
	v_sub_f32_e32 v107, v107, v0
	v_sub_f32_e32 v106, v106, v0
	v_sub_f32_e32 v105, v105, v0
	v_sub_f32_e32 v104, v104, v0
	v_sub_f32_e32 v103, v103, v0
	v_sub_f32_e32 v102, v102, v0
	v_sub_f32_e32 v101, v101, v0
	v_sub_f32_e32 v100, v100, v0
	v_sub_f32_e32 v99, v99, v0
	v_sub_f32_e32 v98, v98, v0
	v_sub_f32_e32 v97, v97, v0
	v_sub_f32_e32 v96, v96, v0
	v_add_f32_e32 v217, v217, v0
	s_branch .LBB0_949

; #define LAS __attribute__((address_space(3)))
; #define FA_LOADK(kt) do { _Pragma("unroll") for (int i_ = 0; i_ < NKI; ++i_) kreg[i_] = *(const u32x4*)(ksrc[i_] + (size_t)(unsigned)(kt) * kstep[i_]); } while (0)
; #define FA_LOADV(kt) do { _Pragma("unroll") for (int i_ = 0; i_ < NVI; ++i_) vreg[i_] = *(const u32x4*)(vsrc0 + (size_t)(unsigned)(kt) * vstep + (size_t)i_ * vrowoff); } while (0)
; #define FA_STOREK(buf) do { _Pragma("unroll") for (int i_ = 0; i_ < NKI; ++i_) { if (kval[i_]) *(LAS u32x4*)(Kl + (buf) * KBUF + kdst[i_]) = kreg[i_]; } } while (0)
; #define FA_STOREV(buf) do { _Pragma("unroll") for (int i_ = 0; i_ < NVI; ++i_) *(LAS u32x4*)(Vl + (buf) * VBUF + vdst0 + i_ * VDSTOFF) = vreg[i_]; } while (0)
;     ...
;     f32x16 zero16;
; #pragma unroll
;     for (int r = 0; r < 16; ++r) zero16[r] = 0.f;
;     f32x16 pA0 = zero16, pA1 = zero16, pB0 = zero16, pB1 = zero16;
;     constexpr bool VPRE = (DV <= 64); constexpr int KD = (DV <= 64) ? 3 : 2;
;     constexpr bool NEGM = (MODE != 1);
;     f32x16 negc = zero16; float cbs = 0.f, pend = 0.f; bool pendf = false;
;     if (NEGM) mrun = 0.f;
;     if (!RES) {
;         u32x4 k2_[NKI];
;         FA_LOADK(kt_lo); FA_LOADV(kt_lo);
; #pragma unroll
;         for (int i_ = 0; i_ < NKI; ++i_) k2_[i_] = *(const u32x4*)(ksrc[i_] + (size_t)(unsigned)(kt_lo + 1) * kstep[i_]);
;         FA_STOREK(0); FA_STOREV(0);
; #pragma unroll
;         for (int i_ = 0; i_ < NKI; ++i_) { if (kval[i_]) *(LAS u32x4*)(Kl + KBUF + kdst[i_]) = k2_[i_]; }
;         __syncthreads();
;         if (NEGM) { if (MODE == 2) {     const int tl0 = 64 * kt_lo; float c0_ = 0.f; if (tl0 + 63 - qw0 <= -128) c0_ = lut[0]; else if (tl0 - (qw0 + 31) >= 128) c0_ = lut[511]; cbs = c0_;
; #pragma unroll
;         for (int r_ = 0; r_ < 16; ++r_) negc[r_] = c0_; } }
;         FA_QK(pA0, pA1, 0, negc);
;         __syncthreads();
;     } else {
;         FA_QK(pA0, pA1, kt_lo - win_lo, zero16);
;     }
.LBB0_965:
	v_and_b32_e32 v22, 31, v19
	s_movk_i32 s0, 0x90
	v_mad_u32_u24 v2, v22, s0, 0
	v_add_u32_e32 v215, v2, v0
	ds_read_b128 v[2:5], v215
	s_waitcnt vmcnt(0)
	ds_read_b128 v[6:9], v215 offset:32
	s_waitcnt lgkmcnt(2)
	v_mov_b32_e32 v113, v112
	v_mov_b32_e32 v114, v112
	v_mov_b32_e32 v115, v112
	v_mov_b32_e32 v116, v112
	v_mov_b32_e32 v117, v112
	v_mov_b32_e32 v118, v112
	v_mov_b32_e32 v119, v112
	v_mov_b32_e32 v120, v112
	v_mov_b32_e32 v121, v112
	v_mov_b32_e32 v122, v112
	v_mov_b32_e32 v123, v112
	v_mov_b32_e32 v124, v112
	v_mov_b32_e32 v125, v112
	v_mov_b32_e32 v126, v112
	v_mov_b32_e32 v127, v112
	v_mov_b64_e32 v[80:81], v[112:113]
	v_mov_b64_e32 v[82:83], v[114:115]
	s_waitcnt lgkmcnt(1)
	v_mfma_f32_32x32x16_bf16 v[128:143], v[2:5], v[184:187], v[112:127]
	ds_read_b128 v[2:5], v215 offset:4608
	v_mov_b64_e32 v[84:85], v[116:117]
	v_mov_b64_e32 v[86:87], v[118:119]
	v_mov_b64_e32 v[88:89], v[120:121]
	v_mov_b64_e32 v[90:91], v[122:123]
	v_mov_b64_e32 v[92:93], v[124:125]
	v_mov_b64_e32 v[94:95], v[126:127]
	ds_read_b128 v[10:13], v215 offset:4640
	s_waitcnt lgkmcnt(2)
	v_mfma_f32_32x32x16_bf16 v[128:143], v[6:9], v[176:179], v[128:143]
	v_lshlrev_b32_e32 v6, 1, v19
	v_and_b32_e32 v16, 32, v6
	v_lshlrev_b32_e32 v6, 3, v19
	v_and_b32_e32 v17, 24, v6
	v_lshlrev_b32_e32 v6, 4, v19
	v_and_b32_e32 v19, 0xc0, v6
	s_movk_i32 s0, 0x4200
	s_waitcnt lgkmcnt(1)
	v_mfma_f32_32x32x16_bf16 v[80:95], v[2:5], v[184:187], v[80:95]
	ds_read_b128 v[2:5], v215 offset:64
	s_add_i32 s29, s29, s4
	v_mad_i64_i32 v[20:21], s[0:1], v20, s0, 0
	s_sub_i32 s16, 0xbf, s29
	s_add_u32 s0, s30, s27
	s_addc_u32 s1, 0, s26
	s_waitcnt lgkmcnt(1)
	v_mfma_f32_32x32x16_bf16 v[80:95], v[10:13], v[176:179], v[80:95]
	ds_read_b128 v[6:9], v215 offset:4672
	ds_read_b128 v[10:13], v215 offset:96
	s_mov_b64 s[14:15], 0
	v_mov_b32_e32 v217, 0
	s_mov_b32 s4, -2
	v_mov_b32_e32 v160, v112
	v_mov_b32_e32 v161, v112
	v_mov_b32_e32 v162, v112
	s_waitcnt lgkmcnt(2)
	v_mfma_f32_32x32x16_bf16 v[128:143], v[2:5], v[180:183], v[128:143]
	v_lshl_or_b32 v2, v18, 8, v19
	v_or3_b32 v2, v2, v16, v17
	ds_read_b128 v[16:19], v215 offset:4704
	v_add_u32_e32 v113, 0, v2
	v_lshl_add_u64 v[2:3], s[0:1], 0, v[20:21]
	v_readlane_b32 s0, v254, 1
	v_lshl_add_u64 v[2:3], v[14:15], 1, v[2:3]
	s_waitcnt lgkmcnt(2)
	v_mfma_f32_32x32x16_bf16 v[80:95], v[6:9], v[180:183], v[80:95]
	v_readlane_b32 s1, v254, 2
	v_mov_b32_e32 v14, v1
	v_mov_b32_e32 v15, v1
	v_lshl_add_u64 v[212:213], s[0:1], 0, v[2:3]
	v_add_lshl_u32 v2, s29, v22, 2
	v_sub_u32_e32 v0, v0, v2
	v_readlane_b32 s0, v254, 5
	s_waitcnt lgkmcnt(1)
	v_mfma_f32_32x32x16_bf16 v[128:143], v[10:13], v[188:191], v[128:143]
	v_mov_b32_e32 v2, v1
	v_add_u32_e32 v216, s0, v0
	v_mov_b32_e32 v0, v1
	v_mov_b32_e32 v3, v1
	v_mov_b32_e32 v4, v1
	v_mov_b32_e32 v5, v1
	v_mov_b32_e32 v6, v1
	s_waitcnt lgkmcnt(0)
	v_mfma_f32_32x32x16_bf16 v[80:95], v[16:19], v[188:191], v[80:95]
	v_mov_b32_e32 v7, v1
	v_mov_b32_e32 v8, v1
	v_mov_b32_e32 v9, v1
	v_mov_b32_e32 v10, v1
	v_mov_b32_e32 v11, v1
	v_mov_b32_e32 v12, v1
	v_mov_b32_e32 v13, v1
	v_mov_b64_e32 v[30:31], v[14:15]
	v_mov_b64_e32 v[46:47], v[14:15]
	v_mov_b64_e32 v[62:63], v[14:15]
	v_mov_b64_e32 v[78:79], v[14:15]
	v_mov_b64_e32 v[28:29], v[12:13]
	v_mov_b64_e32 v[26:27], v[10:11]
	v_mov_b64_e32 v[24:25], v[8:9]
	v_mov_b64_e32 v[22:23], v[6:7]
	v_mov_b64_e32 v[20:21], v[4:5]
	v_mov_b64_e32 v[18:19], v[2:3]
	v_mov_b64_e32 v[16:17], v[0:1]
	v_mov_b64_e32 v[44:45], v[12:13]
	v_mov_b64_e32 v[42:43], v[10:11]
	v_mov_b64_e32 v[40:41], v[8:9]
	v_mov_b64_e32 v[38:39], v[6:7]
	v_mov_b64_e32 v[36:37], v[4:5]
	v_mov_b64_e32 v[34:35], v[2:3]
	v_mov_b64_e32 v[32:33], v[0:1]
	v_mov_b64_e32 v[60:61], v[12:13]
	v_mov_b64_e32 v[58:59], v[10:11]
	v_mov_b64_e32 v[56:57], v[8:9]
	v_mov_b64_e32 v[54:55], v[6:7]
	v_mov_b64_e32 v[52:53], v[4:5]
	v_mov_b64_e32 v[50:51], v[2:3]
	v_mov_b64_e32 v[48:49], v[0:1]
	v_mov_b64_e32 v[76:77], v[12:13]
	v_mov_b64_e32 v[74:75], v[10:11]
	v_mov_b64_e32 v[72:73], v[8:9]
	v_mov_b64_e32 v[70:71], v[6:7]
	v_mov_b64_e32 v[68:69], v[4:5]
	v_mov_b64_e32 v[66:67], v[2:3]
	v_mov_b64_e32 v[64:65], v[0:1]
	v_mov_b32_e32 v15, 0
	v_mov_b32_e32 v0, 0
	v_mov_b32_e32 v163, v112
	v_mov_b32_e32 v164, v112
	v_mov_b32_e32 v165, v112
	v_mov_b32_e32 v166, v112
	v_mov_b32_e32 v167, v112
	v_mov_b32_e32 v168, v112
	v_mov_b32_e32 v169, v112
	v_mov_b32_e32 v170, v112
	v_mov_b32_e32 v171, v112
	v_mov_b32_e32 v172, v112
	v_mov_b32_e32 v173, v112
	v_mov_b32_e32 v174, v112
	v_mov_b32_e32 v175, v112
	v_readlane_b32 s30, v251, 4
	s_barrier
	ds_read_b32 v0, v1 offset:61440
	s_waitcnt lgkmcnt(0)
	v_readfirstlane_b32 s100, v0
	ds_read_b32 v0, v1 offset:63484
	s_waitcnt lgkmcnt(0)
	v_readfirstlane_b32 s101, v0
	v_mov_b32_e32 v0, 0
	v_readlane_b32 s31, v251, 5
	s_add_i32 s0, s16, 0xfffffea2
	s_cmp_lt_u32 s0, 0xfffffea3
	s_cbranch_scc0 .LBB0_971

.LBB0_968:
	s_add_i32 s0, s16, 0xffffff81
	s_cmpk_lt_i32 s0, 0x9f
	v_mov_b32_e32 v0, 0
	s_cbranch_scc1 .LBB0_970
	v_mov_b32_e32 v0, s101

.Lnegc_keep_4:
	s_min_u32 s0, s17, 29
	s_add_i32 s0, s0, 2
	v_mul_u32_u24_e32 v0, s0, v206
	v_add_co_u32_e32 v10, vcc, s93, v212
	v_lshl_add_u64 v[2:3], v[208:209], 0, v[0:1]
	s_nop 0
	v_addc_co_u32_e32 v11, vcc, 0, v213, vcc
	global_load_dwordx4 v[2:5], v[2:3], off
	s_nop 0
	global_load_dwordx4 v[6:9], v[212:213], off
	s_nop 0
	global_load_dwordx4 v[10:13], v[10:11], off
	ds_read_b128 v[96:99], v215 offset:9216
	ds_read_b128 v[196:199], v215 offset:9248
	ds_read_b128 v[114:117], v215 offset:13824
	ds_read_b128 v[200:203], v215 offset:13856
	v_max3_f32 v0, v240, v128, v129
	v_max3_f32 v14, v240, v130, v131
	s_nop 0
	v_max3_f32 v0, v0, v80, v81
	v_max3_f32 v14, v14, v82, v83
	s_waitcnt lgkmcnt(3)
	v_mfma_f32_32x32x16_bf16 v[144:159], v[96:99], v[184:187], v[160:175]
	ds_read_b128 v[192:195], v215 offset:9280
	ds_read_b128 v[118:121], v215 offset:13888
	v_max3_f32 v0, v0, v132, v133
	v_max3_f32 v14, v14, v134, v135
	s_nop 0
	v_max3_f32 v0, v0, v84, v85
	v_max3_f32 v14, v14, v86, v87
	s_waitcnt lgkmcnt(3)
	v_mfma_f32_32x32x16_bf16 v[96:111], v[114:117], v[184:187], v[160:175]
	v_max3_f32 v0, v0, v136, v137
	v_max3_f32 v14, v14, v138, v139
	s_nop 0
	v_max3_f32 v0, v0, v88, v89
	v_max3_f32 v14, v14, v90, v91
	v_mfma_f32_32x32x16_bf16 v[144:159], v[196:199], v[176:179], v[144:159]
	ds_read_b128 v[122:125], v215 offset:9312
	ds_read_b128 v[114:117], v215 offset:13920
	v_max3_f32 v0, v0, v140, v141
	v_max3_f32 v14, v14, v142, v143
	s_nop 0
	v_max3_f32 v0, v0, v92, v93
	v_max3_f32 v14, v14, v94, v95
	s_waitcnt lgkmcnt(4)
	v_mfma_f32_32x32x16_bf16 v[96:111], v[200:203], v[176:179], v[96:111]
	v_max_f32_e32 v0, v0, v14
	s_nop 0
	v_mov_b32_e32 v14, v0
	s_nop 1
	v_permlane32_swap_b32_e32 v0, v14
	v_max_f32_e32 v0, v0, v14
	s_nop 0
	v_cmp_lt_f32_e32 vcc, s2, v0
	v_cmp_gt_f32_e64 s[0:1], s3, v0
	s_or_b64 vcc, vcc, s[0:1]
	s_cmp_lg_u64 vcc, 0
	s_cselect_b64 s[14:15], -1, 0
	s_cbranch_vccz .LBB0_977
	v_cmp_lt_f32_e32 vcc, 0, v0
	s_or_b64 vcc, vcc, s[0:1]
	s_nop 0
	v_cndmask_b32_e32 v0, 0, v0, vcc
	v_exp_f32_e64 v14, -v0
	v_pk_add_f32 v[128:129], v[128:129], v[0:1] op_sel_hi:[1,0] neg_lo:[0,1] neg_hi:[0,1]
	v_pk_add_f32 v[130:131], v[130:131], v[0:1] op_sel_hi:[1,0] neg_lo:[0,1] neg_hi:[0,1]
	v_pk_add_f32 v[132:133], v[132:133], v[0:1] op_sel_hi:[1,0] neg_lo:[0,1] neg_hi:[0,1]
	v_pk_add_f32 v[134:135], v[134:135], v[0:1] op_sel_hi:[1,0] neg_lo:[0,1] neg_hi:[0,1]
	v_pk_add_f32 v[136:137], v[136:137], v[0:1] op_sel_hi:[1,0] neg_lo:[0,1] neg_hi:[0,1]
	v_pk_add_f32 v[138:139], v[138:139], v[0:1] op_sel_hi:[1,0] neg_lo:[0,1] neg_hi:[0,1]
	v_pk_add_f32 v[140:141], v[140:141], v[0:1] op_sel_hi:[1,0] neg_lo:[0,1] neg_hi:[0,1]
	v_pk_add_f32 v[142:143], v[142:143], v[0:1] op_sel_hi:[1,0] neg_lo:[0,1] neg_hi:[0,1]
	v_sub_f32_e32 v95, v95, v0
	v_sub_f32_e32 v94, v94, v0
	v_sub_f32_e32 v93, v93, v0
	v_sub_f32_e32 v92, v92, v0
	v_sub_f32_e32 v91, v91, v0
	v_sub_f32_e32 v90, v90, v0
	v_sub_f32_e32 v89, v89, v0
	v_sub_f32_e32 v88, v88, v0
	v_sub_f32_e32 v87, v87, v0
	v_sub_f32_e32 v86, v86, v0
	v_sub_f32_e32 v85, v85, v0
	v_sub_f32_e32 v84, v84, v0
	v_sub_f32_e32 v83, v83, v0
	v_sub_f32_e32 v82, v82, v0
	v_sub_f32_e32 v81, v81, v0
	v_sub_f32_e32 v80, v80, v0
	v_add_f32_e32 v217, v217, v0
	s_branch .LBB0_978

.LBB0_986:
	s_cmpk_gt_i32 s16, 0xff80
	s_cbranch_scc0 .LBB0_990
	s_sub_i32 s0, s16, 63
	s_cmpk_lt_i32 s0, 0x9f
	v_mov_b32_e32 v0, 0
	s_cbranch_scc1 .LBB0_989
	v_mov_b32_e32 v0, s101

.Lnegc_keep_5:
	s_min_u32 s1, s17, 28
	s_add_i32 s1, s1, 3
	v_mul_u32_u24_e32 v0, s1, v206
	s_min_u32 s0, s0, 31
	v_lshl_add_u64 v[2:3], v[208:209], 0, v[0:1]
	s_mul_i32 s40, s0, 0x108000
	global_load_dwordx4 v[10:13], v[2:3], off
	v_lshl_add_u64 v[2:3], v[210:211], 0, s[40:41]
	v_add_co_u32_e32 v6, vcc, s93, v2
	v_max3_f32 v0, v240, v144, v145
	v_max3_f32 v84, v240, v146, v147
	s_nop 1
	v_addc_co_u32_e32 v7, vcc, 0, v3, vcc
	global_load_dwordx4 v[2:5], v[2:3], off
	s_nop 0
	global_load_dwordx4 v[6:9], v[6:7], off
	ds_read_b128 v[80:83], v215
	ds_read_b128 v[196:199], v215 offset:32
	ds_read_b128 v[116:119], v215 offset:4608
	ds_read_b128 v[200:203], v215 offset:4640
	v_max3_f32 v0, v0, v96, v97
	v_max3_f32 v84, v84, v98, v99
	s_waitcnt lgkmcnt(3)
	v_mfma_f32_32x32x16_bf16 v[128:143], v[80:83], v[184:187], v[160:175]
	ds_read_b128 v[192:195], v215 offset:64
	ds_read_b128 v[120:123], v215 offset:4672
	v_max3_f32 v0, v0, v148, v149
	v_max3_f32 v84, v84, v150, v151
	s_nop 0
	v_max3_f32 v0, v0, v100, v101
	v_max3_f32 v84, v84, v102, v103
	s_nop 0
	v_max3_f32 v80, v84, v154, v155
	v_max3_f32 v0, v0, v152, v153
	s_nop 0
	v_max3_f32 v112, v80, v106, v107
	s_waitcnt lgkmcnt(3)
	v_mfma_f32_32x32x16_bf16 v[80:95], v[116:119], v[184:187], v[160:175]
	v_max3_f32 v0, v0, v104, v105
	v_mfma_f32_32x32x16_bf16 v[128:143], v[196:199], v[176:179], v[128:143]
	ds_read_b128 v[124:127], v215 offset:96
	ds_read_b128 v[116:119], v215 offset:4704
	v_max3_f32 v0, v0, v156, v157
	v_max3_f32 v112, v112, v158, v159
	s_nop 0
	v_max3_f32 v0, v0, v108, v109
	v_max3_f32 v112, v112, v110, v111
	s_waitcnt lgkmcnt(4)
	v_mfma_f32_32x32x16_bf16 v[80:95], v[200:203], v[176:179], v[80:95]
	v_max_f32_e32 v0, v0, v112
	s_nop 0
	v_mov_b32_e32 v112, v0
	s_nop 1
	v_permlane32_swap_b32_e32 v0, v112
	v_max_f32_e32 v0, v0, v112
	s_nop 0
	v_cmp_lt_f32_e32 vcc, s2, v0
	v_cmp_gt_f32_e64 s[0:1], s3, v0
	s_or_b64 vcc, vcc, s[0:1]
	s_cmp_lg_u64 vcc, 0
	s_cselect_b64 s[14:15], -1, 0
	s_cbranch_vccz .LBB0_994
	v_cmp_lt_f32_e32 vcc, 0, v0
	s_or_b64 vcc, vcc, s[0:1]
	s_nop 0
	v_cndmask_b32_e32 v0, 0, v0, vcc
	v_exp_f32_e64 v112, -v0
	v_pk_add_f32 v[144:145], v[144:145], v[0:1] op_sel_hi:[1,0] neg_lo:[0,1] neg_hi:[0,1]
	v_pk_add_f32 v[146:147], v[146:147], v[0:1] op_sel_hi:[1,0] neg_lo:[0,1] neg_hi:[0,1]
	v_pk_add_f32 v[148:149], v[148:149], v[0:1] op_sel_hi:[1,0] neg_lo:[0,1] neg_hi:[0,1]
	v_pk_add_f32 v[150:151], v[150:151], v[0:1] op_sel_hi:[1,0] neg_lo:[0,1] neg_hi:[0,1]
	v_pk_add_f32 v[152:153], v[152:153], v[0:1] op_sel_hi:[1,0] neg_lo:[0,1] neg_hi:[0,1]
	v_pk_add_f32 v[154:155], v[154:155], v[0:1] op_sel_hi:[1,0] neg_lo:[0,1] neg_hi:[0,1]
	v_pk_add_f32 v[156:157], v[156:157], v[0:1] op_sel_hi:[1,0] neg_lo:[0,1] neg_hi:[0,1]
	v_pk_add_f32 v[158:159], v[158:159], v[0:1] op_sel_hi:[1,0] neg_lo:[0,1] neg_hi:[0,1]
	v_sub_f32_e32 v111, v111, v0
	v_sub_f32_e32 v110, v110, v0
	v_sub_f32_e32 v109, v109, v0
	v_sub_f32_e32 v108, v108, v0
	v_sub_f32_e32 v107, v107, v0
	v_sub_f32_e32 v106, v106, v0
	v_sub_f32_e32 v105, v105, v0
	v_sub_f32_e32 v104, v104, v0
	v_sub_f32_e32 v103, v103, v0
	v_sub_f32_e32 v102, v102, v0
	v_sub_f32_e32 v101, v101, v0
	v_sub_f32_e32 v100, v100, v0
	v_sub_f32_e32 v99, v99, v0
	v_sub_f32_e32 v98, v98, v0
	v_sub_f32_e32 v97, v97, v0
	v_sub_f32_e32 v96, v96, v0
	v_add_f32_e32 v217, v217, v0
	s_branch .LBB0_995

; __global__ void __launch_bounds__(512) fwd_megakernel(Args a) {
	.amdhsa_kernel _Z14fwd_megakernel4Args
		.amdhsa_group_segment_fixed_size 0
		.amdhsa_private_segment_fixed_size 0
		.amdhsa_kernarg_size 496
		.amdhsa_user_sgpr_count 2
		.amdhsa_user_sgpr_dispatch_ptr 0
		.amdhsa_user_sgpr_queue_ptr 0
		.amdhsa_user_sgpr_kernarg_segment_ptr 1
		.amdhsa_user_sgpr_dispatch_id 0
		.amdhsa_user_sgpr_kernarg_preload_length 0
		.amdhsa_user_sgpr_kernarg_preload_offset 0
		.amdhsa_user_sgpr_private_segment_size 0
		.amdhsa_uses_dynamic_stack 0
		.amdhsa_enable_private_segment 0
		.amdhsa_system_sgpr_workgroup_id_x 1
		.amdhsa_system_sgpr_workgroup_id_y 0
		.amdhsa_system_sgpr_workgroup_id_z 0
		.amdhsa_system_sgpr_workgroup_info 0
		.amdhsa_system_vgpr_workitem_id 2
		.amdhsa_next_free_vgpr 256
		.amdhsa_next_free_sgpr 102
		.amdhsa_accum_offset 256
		.amdhsa_reserve_vcc 1
		.amdhsa_float_round_mode_32 0
		.amdhsa_float_round_mode_16_64 0
		.amdhsa_float_denorm_mode_32 3
		.amdhsa_float_denorm_mode_16_64 3
		.amdhsa_dx10_clamp 1
		.amdhsa_ieee_mode 1
		.amdhsa_fp16_overflow 0
		.amdhsa_tg_split 0
		.amdhsa_exception_fp_ieee_invalid_op 0
		.amdhsa_exception_fp_denorm_src 0
		.amdhsa_exception_fp_ieee_div_zero 0
		.amdhsa_exception_fp_ieee_overflow 0
		.amdhsa_exception_fp_ieee_underflow 0
		.amdhsa_exception_fp_ieee_inexact 0
		.amdhsa_exception_int_div_zero 0
	.end_amdhsa_kernel

; __global__ void __launch_bounds__(512) fwd_megakernel(Args a) {
amdhsa.kernels:
  - .agpr_count:     0
    .args:
      - .offset:         0
        .size:           240
        .value_kind:     by_value
      - .offset:         240
        .size:           4
        .value_kind:     hidden_block_count_x
      - .offset:         244
        .size:           4
        .value_kind:     hidden_block_count_y
      - .offset:         248
        .size:           4
        .value_kind:     hidden_block_count_z
      - .offset:         252
        .size:           2
        .value_kind:     hidden_group_size_x
      - .offset:         254
        .size:           2
        .value_kind:     hidden_group_size_y
      - .offset:         256
        .size:           2
        .value_kind:     hidden_group_size_z
      - .offset:         258
        .size:           2
        .value_kind:     hidden_remainder_x
      - .offset:         260
        .size:           2
        .value_kind:     hidden_remainder_y
      - .offset:         262
        .size:           2
        .value_kind:     hidden_remainder_z
      - .offset:         280
        .size:           8
        .value_kind:     hidden_global_offset_x
      - .offset:         288
        .size:           8
        .value_kind:     hidden_global_offset_y
      - .offset:         296
        .size:           8
        .value_kind:     hidden_global_offset_z
      - .offset:         304
        .size:           2
        .value_kind:     hidden_grid_dims
      - .offset:         328
        .size:           8
        .value_kind:     hidden_multigrid_sync_arg
      - .offset:         360
        .size:           4
        .value_kind:     hidden_dynamic_lds_size
    .group_segment_fixed_size: 0
    .kernarg_segment_align: 8
    .kernarg_segment_size: 496
    .language:       OpenCL C
    .language_version:
      - 2
      - 0
    .max_flat_workgroup_size: 512
    .name:           _Z14fwd_megakernel4Args
    .private_segment_fixed_size: 0
    .sgpr_count:     108
    .sgpr_spill_count: 376
    .symbol:         _Z14fwd_megakernel4Args.kd
    .uniform_work_group_size: 1
    .uses_dynamic_stack: false
    .vgpr_count:     256
    .vgpr_spill_count: 0
    .wavefront_size: 64
